# attention tile loop: back-edge rotation (guide 7.11) - slot rotation, next-tile LDS bases and active test moved ahead of the per-tile barrier (on v39)
# speedup vs baseline: 1.0075x; 1.0028x over previous
; #define LAS __attribute__((address_space(3)))
; __device__ __forceinline__ unsigned pk(float lo, float hi) { unsigned r; asm("s_nop 0\n\tv_cvt_pk_bf16_f32 %0, %1, %2" : "=v"(r) : "v"(lo), "v"(hi)); return r; }
; template <int DQK, bool MLA> ...
;     ...
;     auto substep = [&](f32x16& a, f32x16& b, int knext_ofs, int vofs, int h, int kafter_ofs) __attribute__((always_inline)) {
;         const LAS unsigned char* kb = lds + knext_ofs + r32 * KPITCH + hi * 16;
;         const LAS unsigned char* vb = lds + vofs + r32 * 144 + hi * 16 + h * 64;
;         u32x4 pw0, pw1; bf16x8 vf0[4], vf1[4], kr[3];
;         kr[0] = kp0; kr[1] = kp1;
;         float rs0 = rs_early;
;         __builtin_amdgcn_sched_barrier(0);
; #pragma unroll
;         for (int d0 = 0; d0 < KS; ++d0) {
;             if (d0 + 2 < KS) kr[(d0 + 2) % 3] = *(const LAS bf16x8*)(kb + (d0 + 2) * 32);
;             if (d0 == KS - 3) {
; #pragma unroll
;                 for (int d = 0; d < 4; ++d) vf0[d] = *(const LAS bf16x8*)(vb + d * 4608);
;             }
;             if (d0 == 0) { const f32x16 z16 = {0.f, 0.f, 0.f, 0.f, 0.f, 0.f, 0.f, 0.f, 0.f, 0.f, 0.f, 0.f, 0.f, 0.f, 0.f, 0.f};
;                 b = __builtin_amdgcn_mfma_f32_32x32x16_bf16(kr[0], qf[0], z16, 0, 0, 0); }
;             else b = __builtin_amdgcn_mfma_f32_32x32x16_bf16(kr[d0 % 3], qf[d0], b, 0, 0, 0);
; #pragma unroll
;             for (int e = 6 + (10 * d0) / KS; e < 6 + (10 * (d0 + 1)) / KS; ++e) {
;                 const float x = __builtin_amdgcn_exp2f(a[e]);
;                 a[e] = x;
;                 rs0 += x;
;                 if (e == 7)  { pw0.x = pk(a[0], a[1]); pw0.y = pk(a[2], a[3]);   pw0.z = pk(a[4], a[5]);   pw0.w = pk(a[6], a[7]); }
;                 if (e == 15) { pw1.x = pk(a[8], a[9]); pw1.y = pk(a[10], a[11]); pw1.z = pk(a[12], a[13]); pw1.w = pk(a[14], a[15]); }
;             }
;             __builtin_amdgcn_sched_barrier(0);
;         }
;     ...
;     for (int t = 0; t < NT; ++t) {
;         const bool has_k2 = (t + 2 < NT), has_v1 = (t + 1 < NT), active = (t <= tmax_w);
;         const int vofs = 3 * KT_BYTES + (t & 1) * VT_BYTES;
;         if (has_k2) gload_k(t + 2);
;         if (has_v1) gload_v(t + 1);
;         if (active) substep(sX, sY, kc + 32 * KPITCH, vofs, 0, kn);
;         if (active) substep(sY, sX, kn, vofs, 1, kn + 32 * KPITCH);
.LBB0_1041:
	s_mov_b32 s72, s71
	s_mov_b32 s71, s34
	s_bitcmp1_b32 s68, 0
	s_cselect_b32 s34, s87, 0x12c00
	v_add_u32_e32 v193, s70, v183
	v_add_u32_e32 v208, s34, v175
	s_cmp_gt_u32 s68, s48
	s_waitcnt lgkmcnt(1)
	s_branch .Lattn_chk
.Lattn_head:
	s_waitcnt lgkmcnt(0)
	s_barrier
.Lattn_chk:
	s_cbranch_scc1 .Lattn_inact
	v_mfma_f32_32x32x16_bf16 v[80:95], v[80:83], v[100:103], 0
	ds_read_b128 v[210:213], v193 offset:12864
	global_load_dwordx4 v[148:151], v[204:205], off
	global_load_dwordx4 v[152:155], v[206:207], off
	v_lshl_add_u64 v[204:205], v[204:205], 0, s[14:15]
	v_lshl_add_u64 v[206:207], v[206:207], 0, s[14:15]
	s_waitcnt lgkmcnt(1)
	v_mfma_f32_32x32x16_bf16 v[80:95], v[160:163], v[104:107], v[80:95]
	v_exp_f32_e32 v70, v70
	ds_read_b128 v[214:217], v193 offset:12896
	v_add_f32_e32 v186, v70, v186
	v_lshl_add_u64 v[234:235], s[26:27], 0, v[202:203]
	global_load_dwordx4 v[156:159], v[234:235], off
	v_lshl_add_u64 v[202:203], v[202:203], 0, s[0:1]
	s_waitcnt lgkmcnt(1)
	v_mfma_f32_32x32x16_bf16 v[80:95], v[210:213], v[108:111], v[80:95]
	ds_read_b128 v[160:163], v193 offset:12928
	v_exp_f32_e32 v71, v71
	v_cvt_pk_bf16_f32 v64, v64, v65
	v_cvt_pk_bf16_f32 v65, v66, v67
	v_cvt_pk_bf16_f32 v66, v68, v69
	v_cvt_pk_bf16_f32 v67, v70, v71
	v_add_f32_e32 v186, v71, v186
	s_waitcnt lgkmcnt(1)
	v_mfma_f32_32x32x16_bf16 v[80:95], v[214:217], v[112:115], v[80:95]
	ds_read_b128 v[68:71], v193 offset:12960
	v_lshl_add_u64 v[234:235], s[26:27], 0, v[190:191]
	v_add_co_u32_e32 v236, vcc, 0x1d204000, v234
	s_nop 1
	v_addc_co_u32_e32 v237, vcc, 0, v235, vcc
	global_load_dwordx4 v[164:167], v[236:237], off offset:2048
	v_exp_f32_e32 v194, v72
	s_nop 0
	v_add_f32_e32 v72, v194, v186
	s_waitcnt lgkmcnt(1)
	v_mfma_f32_32x32x16_bf16 v[80:95], v[160:163], v[116:119], v[80:95]
	v_exp_f32_e32 v186, v73
	ds_read_b128 v[210:213], v193 offset:12992
	v_add_f32_e32 v72, v186, v72
	v_add_co_u32_e32 v236, vcc, 0x1d206000, v234
	s_nop 1
	v_addc_co_u32_e32 v237, vcc, 0, v235, vcc
	global_load_dwordx4 v[168:171], v[236:237], off offset:2048
	s_waitcnt lgkmcnt(1)
	v_mfma_f32_32x32x16_bf16 v[80:95], v[68:71], v[120:123], v[80:95]
	s_and_saveexec_b64 s[34:35], s[4:5]
	s_cbranch_execz .Lattn_ld6_skip
	v_add_co_u32_e32 v236, vcc, 0x1d208000, v234
	s_nop 1
	v_addc_co_u32_e32 v237, vcc, 0, v235, vcc
	global_load_dwordx4 v[96:99], v[236:237], off offset:2048

; template <int DQK, bool MLA> ...
;     ...
;     for (int t = 0; t < NT; ++t) {
;         const bool has_k2 = (t + 2 < NT), has_v1 = (t + 1 < NT), active = (t <= tmax_w);
;         const int vofs = 3 * KT_BYTES + (t & 1) * VT_BYTES;
;         if (has_k2) gload_k(t + 2);
;         if (has_v1) gload_v(t + 1);
;         if (active) substep(sX, sY, kc + 32 * KPITCH, vofs, 0, kn);
;         if (active) substep(sY, sX, kn, vofs, 1, kn + 32 * KPITCH);
;         if (has_k2) sts_k(kn2);
;         if (has_v1) sts_v((t + 1) & 1);
;         __syncthreads();
;         const int tmp = kc; kc = kn; kn = kn2; kn2 = tmp;
.Lattn_wtail:
	s_cmp_eq_u32 s49, s68
	s_cbranch_scc1 .Lattn_exit
	s_mov_b32 s34, s70
	s_mov_b32 s70, s72
	s_mov_b32 s72, s71
	s_mov_b32 s71, s34
	s_bitcmp1_b32 s68, 0
	s_cselect_b32 s34, s87, 0x12c00
	v_add_u32_e32 v193, s70, v183
	v_add_u32_e32 v208, s34, v175
	s_cmp_gt_u32 s68, s48
	s_branch .Lattn_head
